# v181 plus P6 h1b residual loads coalesced through the LDS tile
# baseline (speedup 1.0000x reference)
; __device__ __forceinline__ void unpack8(const u32x4 w, float (&f)[8]) { f[0] = bflo(w.x); f[1] = bfhi(w.x); f[2] = bflo(w.y); f[3] = bfhi(w.y); f[4] = bflo(w.z); f[5] = bfhi(w.z); f[6] = bflo(w.w); f[7] = bfhi(w.w); }
;     __device__ __forceinline__ void operator()(const f32x4 (&acc)[2][2][4][2], const Unit& u, int wr, int wc, int fr, int fq) const {
;         const int row0 = u.pm * BM + wr * 64 + fr, col0 = u.pn * BM + wc * 32 + 8 * fq;
; #pragma unroll
;         for (int ai = 0; ai < 2; ++ai)
; #pragma unroll
;             for (int m = 0; m < 4; ++m) { const size_t idx = (size_t)(row0 + ai * HALF + m * 16) * 1024 + col0;
; #pragma unroll
;                 for (int bj = 0; bj < 2; ++bj) { float h[8]; unpack8(__builtin_nontemporal_load((const u32x4*)(h1b + idx + bj * HALF)), h);
;                     const f32x4 a0 = acc[ai][bj][m][0], a1 = acc[ai][bj][m][1];
;                     __builtin_nontemporal_store(((f32x4){h[0] + a0[0], h[1] + a0[1], h[2] + a0[2], h[3] + a0[3]}), (f32x4*)(out + idx + bj * HALF));
;                     __builtin_nontemporal_store(((f32x4){h[4] + a1[0], h[5] + a1[1], h[6] + a1[2], h[7] + a1[3]}), (f32x4*)(out + idx + bj * HALF + 4)); } }
.LBB0_816:
	v_mbcnt_lo_u32_b32 v224, -1, 0
	v_mbcnt_hi_u32_b32 v224, -1, v224
	v_lshrrev_b32_e32 v226, 2, v224
	v_and_b32_e32 v227, 3, v224
	v_and_or_b32 v232, v150, -16, v226
	v_lshl_add_u32 v232, s28, 8, v232
	v_and_b32_e32 v233, 0xffffffe7, v152
	v_lshl_or_b32 v233, s47, 8, v233
	v_lshl_add_u32 v233, v227, 3, v233
	v_lshl_add_u32 v232, v232, 10, v233
	v_lshlrev_b32_e32 v232, 1, v232
	global_load_dwordx4 v[156:159], v232, s[8:9] nt
	global_load_dwordx4 v[160:163], v232, s[8:9] offset:256 nt
	v_add_u32_e32 v232, 0x8000, v232
	global_load_dwordx4 v[164:167], v232, s[8:9] nt
	global_load_dwordx4 v[168:171], v232, s[8:9] offset:256 nt
	v_add_u32_e32 v232, 0x8000, v232
	global_load_dwordx4 v[172:175], v232, s[8:9] nt
	global_load_dwordx4 v[176:179], v232, s[8:9] offset:256 nt
	v_add_u32_e32 v232, 0x8000, v232
	global_load_dwordx4 v[180:183], v232, s[8:9] nt
	global_load_dwordx4 v[184:187], v232, s[8:9] offset:256 nt
	v_add_u32_e32 v232, 0x28000, v232
	global_load_dwordx4 v[188:191], v232, s[8:9] nt
	global_load_dwordx4 v[192:195], v232, s[8:9] offset:256 nt
	v_add_u32_e32 v232, 0x8000, v232
	global_load_dwordx4 v[196:199], v232, s[8:9] nt
	global_load_dwordx4 v[200:203], v232, s[8:9] offset:256 nt
	v_add_u32_e32 v232, 0x8000, v232
	global_load_dwordx4 v[204:207], v232, s[8:9] nt
	global_load_dwordx4 v[208:211], v232, s[8:9] offset:256 nt
	v_add_u32_e32 v232, 0x8000, v232
	global_load_dwordx4 v[212:215], v232, s[8:9] nt
	global_load_dwordx4 v[216:219], v232, s[8:9] offset:256 nt
	v_mbcnt_lo_u32_b32 v224, -1, 0
	v_mbcnt_hi_u32_b32 v224, -1, v224
	v_bfe_u32 v225, v150, 6, 1
	v_bfe_u32 v226, v152, 5, 2
	v_lshl_or_b32 v225, v225, 2, v226
	v_mul_u32_u24_e32 v225, 0x500, v225
	v_add_u32_e32 v225, 0x20000, v225
	v_and_b32_e32 v226, 7, v150
	v_bfe_u32 v227, v152, 3, 2
	v_lshlrev_b32_e32 v227, 1, v227
	v_xor_b32_e32 v228, v227, v226
	v_lshlrev_b32_e32 v228, 4, v228
	v_lshl_add_u32 v234, v226, 7, v228
	v_add_u32_e32 v234, v234, v225
	v_or_b32_e32 v227, 1, v227
	v_xor_b32_e32 v228, v227, v226
	v_lshlrev_b32_e32 v228, 4, v228
	v_lshl_add_u32 v235, v226, 7, v228
	v_add_u32_e32 v235, v235, v225
	v_lshrrev_b32_e32 v226, 3, v224
	v_and_b32_e32 v227, 7, v224
	v_xor_b32_e32 v228, v227, v226
	v_lshlrev_b32_e32 v228, 4, v228
	v_lshl_add_u32 v236, v226, 7, v228
	v_add_u32_e32 v236, v236, v225
	v_and_b32_e32 v228, 0xfffffff0, v150
	v_add_u32_e32 v228, v228, v226
	v_lshl_add_u32 v228, s28, 8, v228
	v_and_b32_e32 v229, 0xffffffe7, v152
	v_lshl_or_b32 v229, s47, 8, v229
	v_lshl_add_u32 v229, v227, 2, v229
	v_lshl_add_u32 v228, v228, 10, v229
	v_lshlrev_b32_e32 v233, 2, v228
	v_add_u32_e32 v237, 0x8000, v233
	v_and_b32_e32 v226, 15, v150
	v_mul_u32_u24_e32 v220, 0x50, v226
	v_bfe_u32 v227, v152, 3, 2
	v_lshl_add_u32 v220, v227, 4, v220
	v_add_u32_e32 v220, v220, v225
	v_lshrrev_b32_e32 v226, 2, v224
	v_and_b32_e32 v227, 3, v224
	v_mul_u32_u24_e32 v221, 0x50, v226
	v_lshl_add_u32 v221, v227, 4, v221
	v_add_u32_e32 v221, v221, v225
	s_mov_b32 s98, 0x00ff00ff
	s_mov_b32 s99, 0x00ff00ff
	s_mov_b32 s100, 0xff00ff00
	s_mov_b32 s101, 0xff00ff00
	s_waitcnt vmcnt(14)
	ds_write_b128 v221, v[156:159]
	ds_read_b128 v[156:159], v220
	ds_write_b128 v221, v[160:163]
	ds_read_b128 v[160:163], v220
	s_waitcnt lgkmcnt(0)
	v_lshlrev_b32_e32 v224, 16, v156
	v_and_b32_e32 v225, 0xffff0000, v156
	v_lshlrev_b32_e32 v226, 16, v157
	v_and_b32_e32 v227, 0xffff0000, v157
	v_lshlrev_b32_e32 v228, 16, v158
	v_and_b32_e32 v229, 0xffff0000, v158
	v_lshlrev_b32_e32 v230, 16, v159
	v_and_b32_e32 v231, 0xffff0000, v159
	v_pk_add_f32 v[124:125], v[124:125], v[224:225]
	v_pk_add_f32 v[126:127], v[126:127], v[226:227]
	v_pk_add_f32 v[120:121], v[120:121], v[228:229]
	v_pk_add_f32 v[122:123], v[122:123], v[230:231]
	s_mov_b64 exec, s[98:99]
	ds_write_b128 v234, v[124:127]
	ds_write_b128 v235, v[120:123]
	s_mov_b64 exec, -1
	ds_read_b128 v[238:241], v236
	s_mov_b64 exec, s[100:101]
	ds_write_b128 v234, v[124:127]
	ds_write_b128 v235, v[120:123]
	s_mov_b64 exec, -1
	ds_read_b128 v[242:245], v236
	s_waitcnt lgkmcnt(3)
	global_store_dwordx4 v233, v[238:241], s[50:51] nt
	s_waitcnt lgkmcnt(0)
	global_store_dwordx4 v237, v[242:245], s[50:51] nt
	v_lshlrev_b32_e32 v224, 16, v160
	v_and_b32_e32 v225, 0xffff0000, v160
	v_lshlrev_b32_e32 v226, 16, v161
	v_and_b32_e32 v227, 0xffff0000, v161
	v_lshlrev_b32_e32 v228, 16, v162
	v_and_b32_e32 v229, 0xffff0000, v162
	v_lshlrev_b32_e32 v230, 16, v163
	v_and_b32_e32 v231, 0xffff0000, v163
	v_pk_add_f32 v[116:117], v[116:117], v[224:225]
	v_pk_add_f32 v[118:119], v[118:119], v[226:227]
	v_pk_add_f32 v[112:113], v[112:113], v[228:229]
	v_pk_add_f32 v[114:115], v[114:115], v[230:231]
	s_mov_b64 exec, s[98:99]
	ds_write_b128 v234, v[116:119]
	ds_write_b128 v235, v[112:115]
	s_mov_b64 exec, -1
	ds_read_b128 v[238:241], v236
	s_mov_b64 exec, s[100:101]
	ds_write_b128 v234, v[116:119]
	ds_write_b128 v235, v[112:115]
	s_mov_b64 exec, -1
	ds_read_b128 v[242:245], v236
	s_waitcnt lgkmcnt(3)
	global_store_dwordx4 v233, v[238:241], s[50:51] offset:512 nt
	s_waitcnt lgkmcnt(0)
	global_store_dwordx4 v237, v[242:245], s[50:51] offset:512 nt
	v_add_u32_e32 v233, 0x10000, v233
	v_add_u32_e32 v237, 0x10000, v237
	s_waitcnt vmcnt(16)
	ds_write_b128 v221, v[164:167]
	ds_read_b128 v[164:167], v220
	ds_write_b128 v221, v[168:171]
	ds_read_b128 v[168:171], v220
	s_waitcnt lgkmcnt(0)
; __device__ __forceinline__ void unpack8(const u32x4 w, float (&f)[8]) { f[0] = bflo(w.x); f[1] = bfhi(w.x); f[2] = bflo(w.y); f[3] = bfhi(w.y); f[4] = bflo(w.z); f[5] = bfhi(w.z); f[6] = bflo(w.w); f[7] = bfhi(w.w); }
;     __device__ __forceinline__ void operator()(const f32x4 (&acc)[2][2][4][2], const Unit& u, int wr, int wc, int fr, int fq) const {
;         const int row0 = u.pm * BM + wr * 64 + fr, col0 = u.pn * BM + wc * 32 + 8 * fq;
; #pragma unroll
;         for (int ai = 0; ai < 2; ++ai)
; #pragma unroll
;             for (int m = 0; m < 4; ++m) { const size_t idx = (size_t)(row0 + ai * HALF + m * 16) * 1024 + col0;
; #pragma unroll
;                 for (int bj = 0; bj < 2; ++bj) { float h[8]; unpack8(__builtin_nontemporal_load((const u32x4*)(h1b + idx + bj * HALF)), h);
;                     const f32x4 a0 = acc[ai][bj][m][0], a1 = acc[ai][bj][m][1];
;                     __builtin_nontemporal_store(((f32x4){h[0] + a0[0], h[1] + a0[1], h[2] + a0[2], h[3] + a0[3]}), (f32x4*)(out + idx + bj * HALF));
;                     __builtin_nontemporal_store(((f32x4){h[4] + a1[0], h[5] + a1[1], h[6] + a1[2], h[7] + a1[3]}), (f32x4*)(out + idx + bj * HALF + 4)); } }
	v_lshlrev_b32_e32 v224, 16, v164
	v_and_b32_e32 v225, 0xffff0000, v164
	v_lshlrev_b32_e32 v226, 16, v165
	v_and_b32_e32 v227, 0xffff0000, v165
	v_lshlrev_b32_e32 v228, 16, v166
	v_and_b32_e32 v229, 0xffff0000, v166
	v_lshlrev_b32_e32 v230, 16, v167
	v_and_b32_e32 v231, 0xffff0000, v167
	v_pk_add_f32 v[108:109], v[108:109], v[224:225]
	v_pk_add_f32 v[110:111], v[110:111], v[226:227]
	v_pk_add_f32 v[104:105], v[104:105], v[228:229]
	v_pk_add_f32 v[106:107], v[106:107], v[230:231]
	s_mov_b64 exec, s[98:99]
	ds_write_b128 v234, v[108:111]
	ds_write_b128 v235, v[104:107]
	s_mov_b64 exec, -1
	ds_read_b128 v[238:241], v236
	s_mov_b64 exec, s[100:101]
	ds_write_b128 v234, v[108:111]
	ds_write_b128 v235, v[104:107]
	s_mov_b64 exec, -1
	ds_read_b128 v[242:245], v236
	s_waitcnt lgkmcnt(3)
	global_store_dwordx4 v233, v[238:241], s[50:51] nt
	s_waitcnt lgkmcnt(0)
	global_store_dwordx4 v237, v[242:245], s[50:51] nt
	v_lshlrev_b32_e32 v224, 16, v168
	v_and_b32_e32 v225, 0xffff0000, v168
	v_lshlrev_b32_e32 v226, 16, v169
	v_and_b32_e32 v227, 0xffff0000, v169
	v_lshlrev_b32_e32 v228, 16, v170
	v_and_b32_e32 v229, 0xffff0000, v170
	v_lshlrev_b32_e32 v230, 16, v171
	v_and_b32_e32 v231, 0xffff0000, v171
	v_pk_add_f32 v[100:101], v[100:101], v[224:225]
	v_pk_add_f32 v[102:103], v[102:103], v[226:227]
	v_pk_add_f32 v[96:97], v[96:97], v[228:229]
	v_pk_add_f32 v[98:99], v[98:99], v[230:231]
	s_mov_b64 exec, s[98:99]
	ds_write_b128 v234, v[100:103]
	ds_write_b128 v235, v[96:99]
	s_mov_b64 exec, -1
	ds_read_b128 v[238:241], v236
	s_mov_b64 exec, s[100:101]
	ds_write_b128 v234, v[100:103]
	ds_write_b128 v235, v[96:99]
	s_mov_b64 exec, -1
	ds_read_b128 v[242:245], v236
	s_waitcnt lgkmcnt(3)
	global_store_dwordx4 v233, v[238:241], s[50:51] offset:512 nt
	s_waitcnt lgkmcnt(0)
	global_store_dwordx4 v237, v[242:245], s[50:51] offset:512 nt
	v_add_u32_e32 v233, 0x10000, v233
	v_add_u32_e32 v237, 0x10000, v237
	s_waitcnt vmcnt(18)
	ds_write_b128 v221, v[172:175]
	ds_read_b128 v[172:175], v220
	ds_write_b128 v221, v[176:179]
	ds_read_b128 v[176:179], v220
	s_waitcnt lgkmcnt(0)
	v_lshlrev_b32_e32 v224, 16, v172
	v_and_b32_e32 v225, 0xffff0000, v172
	v_lshlrev_b32_e32 v226, 16, v173
	v_and_b32_e32 v227, 0xffff0000, v173
	v_lshlrev_b32_e32 v228, 16, v174
	v_and_b32_e32 v229, 0xffff0000, v174
	v_lshlrev_b32_e32 v230, 16, v175
	v_and_b32_e32 v231, 0xffff0000, v175
	v_pk_add_f32 v[92:93], v[92:93], v[224:225]
	v_pk_add_f32 v[94:95], v[94:95], v[226:227]
	v_pk_add_f32 v[88:89], v[88:89], v[228:229]
	v_pk_add_f32 v[90:91], v[90:91], v[230:231]
	s_mov_b64 exec, s[98:99]
	ds_write_b128 v234, v[92:95]
	ds_write_b128 v235, v[88:91]
	s_mov_b64 exec, -1
	ds_read_b128 v[238:241], v236
	s_mov_b64 exec, s[100:101]
	ds_write_b128 v234, v[92:95]
	ds_write_b128 v235, v[88:91]
	s_mov_b64 exec, -1
	ds_read_b128 v[242:245], v236
	s_waitcnt lgkmcnt(3)
	global_store_dwordx4 v233, v[238:241], s[50:51] nt
	s_waitcnt lgkmcnt(0)
	global_store_dwordx4 v237, v[242:245], s[50:51] nt
	v_lshlrev_b32_e32 v224, 16, v176
	v_and_b32_e32 v225, 0xffff0000, v176
	v_lshlrev_b32_e32 v226, 16, v177
	v_and_b32_e32 v227, 0xffff0000, v177
	v_lshlrev_b32_e32 v228, 16, v178
	v_and_b32_e32 v229, 0xffff0000, v178
	v_lshlrev_b32_e32 v230, 16, v179
	v_and_b32_e32 v231, 0xffff0000, v179
	v_pk_add_f32 v[84:85], v[84:85], v[224:225]
	v_pk_add_f32 v[86:87], v[86:87], v[226:227]
	v_pk_add_f32 v[80:81], v[80:81], v[228:229]
	v_pk_add_f32 v[82:83], v[82:83], v[230:231]
	s_mov_b64 exec, s[98:99]
	ds_write_b128 v234, v[84:87]
	ds_write_b128 v235, v[80:83]
	s_mov_b64 exec, -1
	ds_read_b128 v[238:241], v236
	s_mov_b64 exec, s[100:101]
	ds_write_b128 v234, v[84:87]
	ds_write_b128 v235, v[80:83]
	s_mov_b64 exec, -1
	ds_read_b128 v[242:245], v236
	s_waitcnt lgkmcnt(3)
	global_store_dwordx4 v233, v[238:241], s[50:51] offset:512 nt
	s_waitcnt lgkmcnt(0)
	global_store_dwordx4 v237, v[242:245], s[50:51] offset:512 nt
	v_add_u32_e32 v233, 0x10000, v233
	v_add_u32_e32 v237, 0x10000, v237
	s_waitcnt vmcnt(20)
	ds_write_b128 v221, v[180:183]
	ds_read_b128 v[180:183], v220
	ds_write_b128 v221, v[184:187]
	ds_read_b128 v[184:187], v220
	s_waitcnt lgkmcnt(0)
	v_lshlrev_b32_e32 v224, 16, v180
	v_and_b32_e32 v225, 0xffff0000, v180
	v_lshlrev_b32_e32 v226, 16, v181
	v_and_b32_e32 v227, 0xffff0000, v181
	v_lshlrev_b32_e32 v228, 16, v182
	v_and_b32_e32 v229, 0xffff0000, v182
	v_lshlrev_b32_e32 v230, 16, v183
	v_and_b32_e32 v231, 0xffff0000, v183
	v_pk_add_f32 v[76:77], v[76:77], v[224:225]
	v_pk_add_f32 v[78:79], v[78:79], v[226:227]
	v_pk_add_f32 v[72:73], v[72:73], v[228:229]
	v_pk_add_f32 v[74:75], v[74:75], v[230:231]
	s_mov_b64 exec, s[98:99]
	ds_write_b128 v234, v[76:79]
	ds_write_b128 v235, v[72:75]
	s_mov_b64 exec, -1
	ds_read_b128 v[238:241], v236
	s_mov_b64 exec, s[100:101]
	ds_write_b128 v234, v[76:79]
	ds_write_b128 v235, v[72:75]
	s_mov_b64 exec, -1
	ds_read_b128 v[242:245], v236
	s_waitcnt lgkmcnt(3)
	global_store_dwordx4 v233, v[238:241], s[50:51] nt
	s_waitcnt lgkmcnt(0)
	global_store_dwordx4 v237, v[242:245], s[50:51] nt
	v_lshlrev_b32_e32 v224, 16, v184
	v_and_b32_e32 v225, 0xffff0000, v184
	v_lshlrev_b32_e32 v226, 16, v185
	v_and_b32_e32 v227, 0xffff0000, v185
	v_lshlrev_b32_e32 v228, 16, v186
	v_and_b32_e32 v229, 0xffff0000, v186
	v_lshlrev_b32_e32 v230, 16, v187
	v_and_b32_e32 v231, 0xffff0000, v187
	v_pk_add_f32 v[68:69], v[68:69], v[224:225]
	v_pk_add_f32 v[70:71], v[70:71], v[226:227]
	v_pk_add_f32 v[64:65], v[64:65], v[228:229]
	v_pk_add_f32 v[66:67], v[66:67], v[230:231]
	s_mov_b64 exec, s[98:99]
	ds_write_b128 v234, v[68:71]
	ds_write_b128 v235, v[64:67]
	s_mov_b64 exec, -1
	ds_read_b128 v[238:241], v236
	s_mov_b64 exec, s[100:101]
	ds_write_b128 v234, v[68:71]
	ds_write_b128 v235, v[64:67]
	s_mov_b64 exec, -1
	ds_read_b128 v[242:245], v236
	s_waitcnt lgkmcnt(3)
; __device__ __forceinline__ void unpack8(const u32x4 w, float (&f)[8]) { f[0] = bflo(w.x); f[1] = bfhi(w.x); f[2] = bflo(w.y); f[3] = bfhi(w.y); f[4] = bflo(w.z); f[5] = bfhi(w.z); f[6] = bflo(w.w); f[7] = bfhi(w.w); }
;     __device__ __forceinline__ void operator()(const f32x4 (&acc)[2][2][4][2], const Unit& u, int wr, int wc, int fr, int fq) const {
;         const int row0 = u.pm * BM + wr * 64 + fr, col0 = u.pn * BM + wc * 32 + 8 * fq;
; #pragma unroll
;         for (int ai = 0; ai < 2; ++ai)
; #pragma unroll
;             for (int m = 0; m < 4; ++m) { const size_t idx = (size_t)(row0 + ai * HALF + m * 16) * 1024 + col0;
; #pragma unroll
;                 for (int bj = 0; bj < 2; ++bj) { float h[8]; unpack8(__builtin_nontemporal_load((const u32x4*)(h1b + idx + bj * HALF)), h);
;                     const f32x4 a0 = acc[ai][bj][m][0], a1 = acc[ai][bj][m][1];
;                     __builtin_nontemporal_store(((f32x4){h[0] + a0[0], h[1] + a0[1], h[2] + a0[2], h[3] + a0[3]}), (f32x4*)(out + idx + bj * HALF));
;                     __builtin_nontemporal_store(((f32x4){h[4] + a1[0], h[5] + a1[1], h[6] + a1[2], h[7] + a1[3]}), (f32x4*)(out + idx + bj * HALF + 4)); } }
	global_store_dwordx4 v233, v[238:241], s[50:51] offset:512 nt
	s_waitcnt lgkmcnt(0)
	global_store_dwordx4 v237, v[242:245], s[50:51] offset:512 nt
	v_add_u32_e32 v233, 0x50000, v233
	v_add_u32_e32 v237, 0x50000, v237
	s_waitcnt vmcnt(22)
	ds_write_b128 v221, v[188:191]
	ds_read_b128 v[188:191], v220
	ds_write_b128 v221, v[192:195]
	ds_read_b128 v[192:195], v220
	s_waitcnt lgkmcnt(0)
	v_lshlrev_b32_e32 v224, 16, v188
	v_and_b32_e32 v225, 0xffff0000, v188
	v_lshlrev_b32_e32 v226, 16, v189
	v_and_b32_e32 v227, 0xffff0000, v189
	v_lshlrev_b32_e32 v228, 16, v190
	v_and_b32_e32 v229, 0xffff0000, v190
	v_lshlrev_b32_e32 v230, 16, v191
	v_and_b32_e32 v231, 0xffff0000, v191
	v_pk_add_f32 v[60:61], v[60:61], v[224:225]
	v_pk_add_f32 v[62:63], v[62:63], v[226:227]
	v_pk_add_f32 v[56:57], v[56:57], v[228:229]
	v_pk_add_f32 v[58:59], v[58:59], v[230:231]
	s_mov_b64 exec, s[98:99]
	ds_write_b128 v234, v[60:63]
	ds_write_b128 v235, v[56:59]
	s_mov_b64 exec, -1
	ds_read_b128 v[238:241], v236
	s_mov_b64 exec, s[100:101]
	ds_write_b128 v234, v[60:63]
	ds_write_b128 v235, v[56:59]
	s_mov_b64 exec, -1
	ds_read_b128 v[242:245], v236
	s_waitcnt lgkmcnt(3)
	global_store_dwordx4 v233, v[238:241], s[50:51] nt
	s_waitcnt lgkmcnt(0)
	global_store_dwordx4 v237, v[242:245], s[50:51] nt
	v_lshlrev_b32_e32 v224, 16, v192
	v_and_b32_e32 v225, 0xffff0000, v192
	v_lshlrev_b32_e32 v226, 16, v193
	v_and_b32_e32 v227, 0xffff0000, v193
	v_lshlrev_b32_e32 v228, 16, v194
	v_and_b32_e32 v229, 0xffff0000, v194
	v_lshlrev_b32_e32 v230, 16, v195
	v_and_b32_e32 v231, 0xffff0000, v195
	v_pk_add_f32 v[52:53], v[52:53], v[224:225]
	v_pk_add_f32 v[54:55], v[54:55], v[226:227]
	v_pk_add_f32 v[48:49], v[48:49], v[228:229]
	v_pk_add_f32 v[50:51], v[50:51], v[230:231]
	s_mov_b64 exec, s[98:99]
	ds_write_b128 v234, v[52:55]
	ds_write_b128 v235, v[48:51]
	s_mov_b64 exec, -1
	ds_read_b128 v[238:241], v236
	s_mov_b64 exec, s[100:101]
	ds_write_b128 v234, v[52:55]
	ds_write_b128 v235, v[48:51]
	s_mov_b64 exec, -1
	ds_read_b128 v[242:245], v236
	s_waitcnt lgkmcnt(3)
	global_store_dwordx4 v233, v[238:241], s[50:51] offset:512 nt
	s_waitcnt lgkmcnt(0)
	global_store_dwordx4 v237, v[242:245], s[50:51] offset:512 nt
	v_add_u32_e32 v233, 0x10000, v233
	v_add_u32_e32 v237, 0x10000, v237
	s_waitcnt vmcnt(24)
	ds_write_b128 v221, v[196:199]
	ds_read_b128 v[196:199], v220
	ds_write_b128 v221, v[200:203]
	ds_read_b128 v[200:203], v220
	s_waitcnt lgkmcnt(0)
	v_lshlrev_b32_e32 v224, 16, v196
	v_and_b32_e32 v225, 0xffff0000, v196
	v_lshlrev_b32_e32 v226, 16, v197
	v_and_b32_e32 v227, 0xffff0000, v197
	v_lshlrev_b32_e32 v228, 16, v198
	v_and_b32_e32 v229, 0xffff0000, v198
	v_lshlrev_b32_e32 v230, 16, v199
	v_and_b32_e32 v231, 0xffff0000, v199
	v_pk_add_f32 v[44:45], v[44:45], v[224:225]
	v_pk_add_f32 v[46:47], v[46:47], v[226:227]
	v_pk_add_f32 v[40:41], v[40:41], v[228:229]
	v_pk_add_f32 v[42:43], v[42:43], v[230:231]
	s_mov_b64 exec, s[98:99]
	ds_write_b128 v234, v[44:47]
	ds_write_b128 v235, v[40:43]
	s_mov_b64 exec, -1
	ds_read_b128 v[238:241], v236
	s_mov_b64 exec, s[100:101]
	ds_write_b128 v234, v[44:47]
	ds_write_b128 v235, v[40:43]
	s_mov_b64 exec, -1
	ds_read_b128 v[242:245], v236
	s_waitcnt lgkmcnt(3)
	global_store_dwordx4 v233, v[238:241], s[50:51] nt
	s_waitcnt lgkmcnt(0)
	global_store_dwordx4 v237, v[242:245], s[50:51] nt
	v_lshlrev_b32_e32 v224, 16, v200
	v_and_b32_e32 v225, 0xffff0000, v200
	v_lshlrev_b32_e32 v226, 16, v201
	v_and_b32_e32 v227, 0xffff0000, v201
	v_lshlrev_b32_e32 v228, 16, v202
	v_and_b32_e32 v229, 0xffff0000, v202
	v_lshlrev_b32_e32 v230, 16, v203
	v_and_b32_e32 v231, 0xffff0000, v203
	v_pk_add_f32 v[36:37], v[36:37], v[224:225]
	v_pk_add_f32 v[38:39], v[38:39], v[226:227]
	v_pk_add_f32 v[32:33], v[32:33], v[228:229]
	v_pk_add_f32 v[34:35], v[34:35], v[230:231]
	s_mov_b64 exec, s[98:99]
	ds_write_b128 v234, v[36:39]
	ds_write_b128 v235, v[32:35]
	s_mov_b64 exec, -1
	ds_read_b128 v[238:241], v236
	s_mov_b64 exec, s[100:101]
	ds_write_b128 v234, v[36:39]
	ds_write_b128 v235, v[32:35]
	s_mov_b64 exec, -1
	ds_read_b128 v[242:245], v236
	s_waitcnt lgkmcnt(3)
	global_store_dwordx4 v233, v[238:241], s[50:51] offset:512 nt
	s_waitcnt lgkmcnt(0)
; __device__ __forceinline__ void unpack8(const u32x4 w, float (&f)[8]) { f[0] = bflo(w.x); f[1] = bfhi(w.x); f[2] = bflo(w.y); f[3] = bfhi(w.y); f[4] = bflo(w.z); f[5] = bfhi(w.z); f[6] = bflo(w.w); f[7] = bfhi(w.w); }
;     __device__ __forceinline__ void operator()(const f32x4 (&acc)[2][2][4][2], const Unit& u, int wr, int wc, int fr, int fq) const {
;         const int row0 = u.pm * BM + wr * 64 + fr, col0 = u.pn * BM + wc * 32 + 8 * fq;
; #pragma unroll
;         for (int ai = 0; ai < 2; ++ai)
; #pragma unroll
;             for (int m = 0; m < 4; ++m) { const size_t idx = (size_t)(row0 + ai * HALF + m * 16) * 1024 + col0;
; #pragma unroll
;                 for (int bj = 0; bj < 2; ++bj) { float h[8]; unpack8(__builtin_nontemporal_load((const u32x4*)(h1b + idx + bj * HALF)), h);
;                     const f32x4 a0 = acc[ai][bj][m][0], a1 = acc[ai][bj][m][1];
;                     __builtin_nontemporal_store(((f32x4){h[0] + a0[0], h[1] + a0[1], h[2] + a0[2], h[3] + a0[3]}), (f32x4*)(out + idx + bj * HALF));
;                     __builtin_nontemporal_store(((f32x4){h[4] + a1[0], h[5] + a1[1], h[6] + a1[2], h[7] + a1[3]}), (f32x4*)(out + idx + bj * HALF + 4)); } }
	global_store_dwordx4 v237, v[242:245], s[50:51] offset:512 nt
	v_add_u32_e32 v233, 0x10000, v233
	v_add_u32_e32 v237, 0x10000, v237
	s_waitcnt vmcnt(26)
	ds_write_b128 v221, v[204:207]
	ds_read_b128 v[204:207], v220
	ds_write_b128 v221, v[208:211]
	ds_read_b128 v[208:211], v220
	s_waitcnt lgkmcnt(0)
	v_lshlrev_b32_e32 v224, 16, v204
	v_and_b32_e32 v225, 0xffff0000, v204
	v_lshlrev_b32_e32 v226, 16, v205
	v_and_b32_e32 v227, 0xffff0000, v205
	v_lshlrev_b32_e32 v228, 16, v206
	v_and_b32_e32 v229, 0xffff0000, v206
	v_lshlrev_b32_e32 v230, 16, v207
	v_and_b32_e32 v231, 0xffff0000, v207
	v_pk_add_f32 v[28:29], v[28:29], v[224:225]
	v_pk_add_f32 v[30:31], v[30:31], v[226:227]
	v_pk_add_f32 v[24:25], v[24:25], v[228:229]
	v_pk_add_f32 v[26:27], v[26:27], v[230:231]
	s_mov_b64 exec, s[98:99]
	ds_write_b128 v234, v[28:31]
	ds_write_b128 v235, v[24:27]
	s_mov_b64 exec, -1
	ds_read_b128 v[238:241], v236
	s_mov_b64 exec, s[100:101]
	ds_write_b128 v234, v[28:31]
	ds_write_b128 v235, v[24:27]
	s_mov_b64 exec, -1
	ds_read_b128 v[242:245], v236
	s_waitcnt lgkmcnt(3)
	global_store_dwordx4 v233, v[238:241], s[50:51] nt
	s_waitcnt lgkmcnt(0)
	global_store_dwordx4 v237, v[242:245], s[50:51] nt
	v_lshlrev_b32_e32 v224, 16, v208
	v_and_b32_e32 v225, 0xffff0000, v208
	v_lshlrev_b32_e32 v226, 16, v209
	v_and_b32_e32 v227, 0xffff0000, v209
	v_lshlrev_b32_e32 v228, 16, v210
	v_and_b32_e32 v229, 0xffff0000, v210
	v_lshlrev_b32_e32 v230, 16, v211
	v_and_b32_e32 v231, 0xffff0000, v211
	v_pk_add_f32 v[20:21], v[20:21], v[224:225]
	v_pk_add_f32 v[22:23], v[22:23], v[226:227]
	v_pk_add_f32 v[16:17], v[16:17], v[228:229]
	v_pk_add_f32 v[18:19], v[18:19], v[230:231]
	s_mov_b64 exec, s[98:99]
	ds_write_b128 v234, v[20:23]
	ds_write_b128 v235, v[16:19]
	s_mov_b64 exec, -1
	ds_read_b128 v[238:241], v236
	s_mov_b64 exec, s[100:101]
	ds_write_b128 v234, v[20:23]
	ds_write_b128 v235, v[16:19]
	s_mov_b64 exec, -1
	ds_read_b128 v[242:245], v236
	s_waitcnt lgkmcnt(3)
	global_store_dwordx4 v233, v[238:241], s[50:51] offset:512 nt
	s_waitcnt lgkmcnt(0)
	global_store_dwordx4 v237, v[242:245], s[50:51] offset:512 nt
	v_add_u32_e32 v233, 0x10000, v233
	v_add_u32_e32 v237, 0x10000, v237
	s_waitcnt vmcnt(28)
	ds_write_b128 v221, v[212:215]
	ds_read_b128 v[212:215], v220
	ds_write_b128 v221, v[216:219]
	ds_read_b128 v[216:219], v220
	s_waitcnt lgkmcnt(0)
	v_lshlrev_b32_e32 v224, 16, v212
	v_and_b32_e32 v225, 0xffff0000, v212
	v_lshlrev_b32_e32 v226, 16, v213
	v_and_b32_e32 v227, 0xffff0000, v213
	v_lshlrev_b32_e32 v228, 16, v214
	v_and_b32_e32 v229, 0xffff0000, v214
	v_lshlrev_b32_e32 v230, 16, v215
	v_and_b32_e32 v231, 0xffff0000, v215
	v_pk_add_f32 v[12:13], v[12:13], v[224:225]
	v_pk_add_f32 v[14:15], v[14:15], v[226:227]
	v_pk_add_f32 v[8:9], v[8:9], v[228:229]
	v_pk_add_f32 v[10:11], v[10:11], v[230:231]
	s_mov_b64 exec, s[98:99]
	ds_write_b128 v234, v[12:15]
	ds_write_b128 v235, v[8:11]
	s_mov_b64 exec, -1
	ds_read_b128 v[238:241], v236
	s_mov_b64 exec, s[100:101]
	ds_write_b128 v234, v[12:15]
	ds_write_b128 v235, v[8:11]
	s_mov_b64 exec, -1
	ds_read_b128 v[242:245], v236
	s_waitcnt lgkmcnt(3)
	global_store_dwordx4 v233, v[238:241], s[50:51] nt
	s_waitcnt lgkmcnt(0)
	global_store_dwordx4 v237, v[242:245], s[50:51] nt
	v_lshlrev_b32_e32 v224, 16, v216
	v_and_b32_e32 v225, 0xffff0000, v216
	v_lshlrev_b32_e32 v226, 16, v217
	v_and_b32_e32 v227, 0xffff0000, v217
	v_lshlrev_b32_e32 v228, 16, v218
	v_and_b32_e32 v229, 0xffff0000, v218
	v_lshlrev_b32_e32 v230, 16, v219
	v_and_b32_e32 v231, 0xffff0000, v219
	v_pk_add_f32 v[4:5], v[4:5], v[224:225]
	v_pk_add_f32 v[6:7], v[6:7], v[226:227]
	v_pk_add_f32 v[0:1], v[0:1], v[228:229]
	v_pk_add_f32 v[2:3], v[2:3], v[230:231]
	s_mov_b64 exec, s[98:99]
	ds_write_b128 v234, v[4:7]
	ds_write_b128 v235, v[0:3]
	s_mov_b64 exec, -1
	ds_read_b128 v[238:241], v236
	s_mov_b64 exec, s[100:101]
	ds_write_b128 v234, v[4:7]
	ds_write_b128 v235, v[0:3]
	s_mov_b64 exec, -1
	ds_read_b128 v[242:245], v236
	s_waitcnt lgkmcnt(3)
	global_store_dwordx4 v233, v[238:241], s[50:51] offset:512 nt
	s_waitcnt lgkmcnt(0)
	global_store_dwordx4 v237, v[242:245], s[50:51] offset:512 nt
	s_andn2_b64 vcc, exec, s[0:1]
	s_mov_b64 s[0:1], -1
	s_cbranch_vccnz .LBB0_805
	s_andn2_b64 vcc, exec, s[4:5]
	s_cbranch_vccnz .LBB0_804
	s_barrier
	s_branch .LBB0_804
